# retention chunk-state stores coalesced: each wave transposes its 8 KB output block through a private conflict-free LDS region (row stride 272 B) and writes it with 16 fully contiguous 1 KB stores inst
# speedup vs baseline: 1.0104x; 1.0012x over previous
; #define LAS __attribute__((address_space(3)))
; __device__ __forceinline__ unsigned cvt_pk_bf16(float lo, float hi) { f32x2 v = {lo, hi}; bf16x2_t b = __builtin_convertvector(v, bf16x2_t); return __builtin_bit_cast(unsigned, b); }
; __device__ __forceinline__ float bf_lo(unsigned u) { return __uint_as_float(u << 16); }
; __device__ __forceinline__ float bf_hi(unsigned u) { return __uint_as_float(u & 0xffff0000u); }
; __device__ void ret_state_item(const bf16_t* __restrict__ Kb, const bf16_t* __restrict__ Vb, bf16_t* __restrict__ STf, bf16_t* __restrict__ STb,
;                                int cidx, int head, float lgf2, float lgb2, LAS unsigned char* lds) {
;     ...
;   for (int it = 0; it < 8; ++it) { const int q = tid + it * 512, j = q >> 5, c = q & 31;
;     *(LAS u32x4*)(lds + j * VS + c * 16) = *(const u32x4*)(Vb + (size_t)(row0 + j) * 1024 + head * 256 + c * 8); }
; #pragma unroll
;   for (int it = 0; it < 4; ++it) { const int q = tid + it * 512, j = q >> 4, c = q & 15;
;     const u32x4 v = *(const u32x4*)(Kb + (size_t)(row0 + j) * 512 + head * 128 + c * 8);
;     const float zf = __builtin_amdgcn_exp2f(lgf2 * (float)(127 - j)), zb = __builtin_amdgcn_exp2f(lgb2 * (float)j);
;     u32x4 of, ob;
; #pragma unroll
;     for (int i = 0; i < 4; ++i) { const float a = bf_lo(v[i]), b = bf_hi(v[i]); of[i] = cvt_pk_bf16(a * zf, b * zf); ob[i] = cvt_pk_bf16(a * zb, b * zb); }
;     *(LAS u32x4*)(lds + OKF + j * KS + c * 16) = of; *(LAS u32x4*)(lds + OKB + j * KS + c * 16) = ob; }
.LBB0_437:
	v_mov_b32_e32 v152, v214
	s_and_b32 s12, s6, 0xffffff80
	s_lshl_b32 s20, s13, 8
	s_lshl_b32 s13, s13, 9
	v_ashrrev_i32_e32 v13, 5, v152
	v_and_b32_e32 v153, 31, v152
	s_add_u32 s34, s14, s13
	v_add_u32_e32 v2, s12, v13
	s_addc_u32 s35, s15, 0
	v_lshlrev_b32_e32 v160, 4, v153
	v_ashrrev_i32_e32 v3, 31, v2
	v_lshl_add_u64 v[0:1], s[34:35], 0, v[160:161]
	v_lshlrev_b64 v[2:3], 11, v[2:3]
	v_add_u32_e32 v47, 0x200, v152
	v_lshl_add_u64 v[2:3], v[0:1], 0, v[2:3]
	v_ashrrev_i32_e32 v50, 5, v47
	global_load_dwordx4 v[14:17], v[2:3], off
	v_add_u32_e32 v2, s12, v50
	v_ashrrev_i32_e32 v3, 31, v2
	v_lshlrev_b64 v[2:3], 11, v[2:3]
	v_add_u32_e32 v52, 0x400, v152
	v_lshl_add_u64 v[2:3], v[0:1], 0, v[2:3]
	v_ashrrev_i32_e32 v53, 5, v52
	global_load_dwordx4 v[18:21], v[2:3], off
	v_add_u32_e32 v2, s12, v53
	v_ashrrev_i32_e32 v3, 31, v2
	v_lshlrev_b64 v[2:3], 11, v[2:3]
	v_add_u32_e32 v12, 0x600, v152
	v_lshl_add_u64 v[2:3], v[0:1], 0, v[2:3]
	v_ashrrev_i32_e32 v54, 5, v12
	global_load_dwordx4 v[22:25], v[2:3], off
	v_add_u32_e32 v2, s12, v54
	v_ashrrev_i32_e32 v3, 31, v2
	v_lshlrev_b64 v[2:3], 11, v[2:3]
	v_lshl_add_u64 v[2:3], v[0:1], 0, v[2:3]
	global_load_dwordx4 v[26:29], v[2:3], off
	v_add_u32_e32 v2, 0x800, v152
	v_ashrrev_i32_e32 v55, 5, v2
	v_add_u32_e32 v2, s12, v55
	v_ashrrev_i32_e32 v3, 31, v2
	v_lshlrev_b64 v[2:3], 11, v[2:3]
	v_lshl_add_u64 v[2:3], v[0:1], 0, v[2:3]
	global_load_dwordx4 v[30:33], v[2:3], off
	v_add_u32_e32 v2, 0xa00, v152
	v_ashrrev_i32_e32 v56, 5, v2
	v_add_u32_e32 v2, s12, v56
	v_ashrrev_i32_e32 v3, 31, v2
	v_lshlrev_b64 v[2:3], 11, v[2:3]
	v_lshl_add_u64 v[2:3], v[0:1], 0, v[2:3]
	global_load_dwordx4 v[34:37], v[2:3], off
	v_add_u32_e32 v2, 0xc00, v152
	v_ashrrev_i32_e32 v57, 5, v2
	v_add_u32_e32 v2, s12, v57
	v_ashrrev_i32_e32 v3, 31, v2
	v_lshlrev_b64 v[2:3], 11, v[2:3]
	v_lshl_add_u64 v[2:3], v[0:1], 0, v[2:3]
	global_load_dwordx4 v[38:41], v[2:3], off
	v_add_u32_e32 v2, 0xe00, v152
	v_ashrrev_i32_e32 v58, 5, v2
	v_add_u32_e32 v2, s12, v58
	v_ashrrev_i32_e32 v3, 31, v2
	v_lshlrev_b64 v[2:3], 11, v[2:3]
	v_lshl_add_u64 v[0:1], v[0:1], 0, v[2:3]
	global_load_dwordx4 v[42:45], v[0:1], off
	v_lshlrev_b32_e32 v0, 4, v152
	v_ashrrev_i32_e32 v59, 4, v152
	v_add_u32_e32 v46, 0, v160
	s_add_u32 s34, s52, s20
	v_and_b32_e32 v160, 0xf0, v0
	v_add_u32_e32 v0, s12, v59
	s_addc_u32 s35, s62, 0
	v_ashrrev_i32_e32 v1, 31, v0
	v_lshl_add_u64 v[8:9], s[34:35], 0, v[160:161]
	v_lshlrev_b64 v[0:1], 10, v[0:1]
	v_lshl_add_u64 v[0:1], v[8:9], 0, v[0:1]
	global_load_dwordx4 v[4:7], v[0:1], off
	v_ashrrev_i32_e32 v47, 4, v47
	v_add_u32_e32 v0, s12, v47
	v_ashrrev_i32_e32 v1, 31, v0
	v_lshlrev_b64 v[0:1], 10, v[0:1]
	v_lshl_add_u64 v[0:1], v[8:9], 0, v[0:1]
	global_load_dwordx4 v[0:3], v[0:1], off
	v_ashrrev_i32_e32 v190, 4, v52
	v_add_u32_e32 v190, s12, v190
	v_ashrrev_i32_e32 v191, 31, v190
	v_lshlrev_b64 v[190:191], 10, v[190:191]
	v_lshl_add_u64 v[190:191], v[8:9], 0, v[190:191]
	global_load_dwordx4 v[182:185], v[190:191], off
	v_ashrrev_i32_e32 v190, 4, v12
	v_add_u32_e32 v190, s12, v190
	v_ashrrev_i32_e32 v191, 31, v190
	v_lshlrev_b64 v[190:191], 10, v[190:191]
	v_lshl_add_u64 v[190:191], v[8:9], 0, v[190:191]
	global_load_dwordx4 v[186:189], v[190:191], off
	v_mad_u64_u32 v[48:49], s[34:35], v13, s54, v[46:47]
	v_mad_u64_u32 v[50:51], s[34:35], v50, s54, v[46:47]
	v_sub_u32_e32 v13, 0x7f, v59
	v_cvt_f32_i32_e32 v13, v13
	s_waitcnt vmcnt(11)
	ds_write_b128 v48, v[14:17]
	s_waitcnt vmcnt(10)
	ds_write_b128 v50, v[18:21]
	v_mad_u64_u32 v[14:15], s[34:35], v53, s54, v[46:47]
	v_mul_f32_e32 v13, v10, v13
	s_add_i32 s13, 0, 0x12000
	s_add_i32 s7, s7, s90
	s_waitcnt vmcnt(9)
	ds_write_b128 v14, v[22:25]
	v_mad_u64_u32 v[14:15], s[34:35], v54, s54, v[46:47]
	v_exp_f32_e32 v22, v13
	v_add_u32_e32 v25, s13, v160
	s_waitcnt vmcnt(8)
	ds_write_b128 v14, v[26:29]
	v_mad_u64_u32 v[14:15], s[34:35], v55, s54, v[46:47]
	v_ashrrev_i32_e32 v29, 4, v52
	s_add_i32 s13, 0, 0x1c000
	v_add_u32_e32 v28, s13, v160
	s_movk_i32 s13, 0x140
	s_waitcnt vmcnt(7)
	ds_write_b128 v14, v[30:33]
	v_mad_u64_u32 v[14:15], s[34:35], v56, s54, v[46:47]
	s_waitcnt vmcnt(6)
	ds_write_b128 v14, v[34:37]
	v_mad_u64_u32 v[14:15], s[34:35], v57, s54, v[46:47]
	s_waitcnt vmcnt(5)
	ds_write_b128 v14, v[38:41]
	v_mad_u64_u32 v[14:15], s[34:35], v58, s54, v[46:47]
	s_waitcnt vmcnt(4)
	ds_write_b128 v14, v[42:45]
	v_cvt_f32_i32_e32 v14, v59
	v_mul_f32_e32 v13, v11, v14
	v_exp_f32_e32 v24, v13
	s_waitcnt vmcnt(3)
	v_lshlrev_b32_e32 v18, 16, v4
	v_and_b32_e32 v19, 0xffff0000, v4
	v_pk_mul_f32 v[20:21], v[22:23], v[18:19] op_sel_hi:[0,1]
	v_cvt_pk_bf16_f32 v4, v20, v21
	v_lshlrev_b32_e32 v20, 16, v5
	v_and_b32_e32 v21, 0xffff0000, v5
	v_pk_mul_f32 v[18:19], v[24:25], v[18:19] op_sel_hi:[0,1]
	v_pk_mul_f32 v[26:27], v[22:23], v[20:21] op_sel_hi:[0,1]
	v_pk_mul_f32 v[20:21], v[24:25], v[20:21] op_sel_hi:[0,1]
	v_cvt_pk_bf16_f32 v18, v18, v19
	v_cvt_pk_bf16_f32 v19, v20, v21
	v_lshlrev_b32_e32 v20, 16, v6
	v_and_b32_e32 v21, 0xffff0000, v6
	v_cvt_pk_bf16_f32 v5, v26, v27
	v_pk_mul_f32 v[26:27], v[22:23], v[20:21] op_sel_hi:[0,1]
	v_cvt_pk_bf16_f32 v6, v26, v27
	v_lshlrev_b32_e32 v26, 16, v7
	v_and_b32_e32 v27, 0xffff0000, v7
	v_pk_mul_f32 v[22:23], v[22:23], v[26:27] op_sel_hi:[0,1]
	v_pk_mul_f32 v[20:21], v[24:25], v[20:21] op_sel_hi:[0,1]
	v_cvt_pk_bf16_f32 v7, v22, v23
	v_pk_mul_f32 v[22:23], v[24:25], v[26:27] op_sel_hi:[0,1]
	v_mul_lo_u32 v13, v59, s13
	v_cvt_pk_bf16_f32 v20, v20, v21
	v_cvt_pk_bf16_f32 v21, v22, v23
	v_add_u32_e32 v22, v25, v13
	ds_write_b128 v22, v[4:7]
	v_sub_u32_e32 v4, 0x7f, v47
	v_ashrrev_i32_e32 v24, 4, v12
	v_cvt_f32_i32_e32 v22, v4
	v_cvt_f32_i32_e32 v9, v47
	v_add_u32_e32 v8, v28, v13
	ds_write_b128 v8, v[18:21]
	v_mul_f32_e32 v8, v10, v22
	v_exp_f32_e32 v8, v8
	v_mul_f32_e32 v9, v11, v9
	v_exp_f32_e32 v12, v9
	s_waitcnt vmcnt(2)
; #define LAS __attribute__((address_space(3)))
; __device__ __forceinline__ unsigned cvt_pk_bf16(float lo, float hi) { f32x2 v = {lo, hi}; bf16x2_t b = __builtin_convertvector(v, bf16x2_t); return __builtin_bit_cast(unsigned, b); }
; __device__ __forceinline__ float bf_lo(unsigned u) { return __uint_as_float(u << 16); }
; __device__ __forceinline__ float bf_hi(unsigned u) { return __uint_as_float(u & 0xffff0000u); }
; __device__ void ret_state_item(const bf16_t* __restrict__ Kb, const bf16_t* __restrict__ Vb, bf16_t* __restrict__ STf, bf16_t* __restrict__ STb,
;                                int cidx, int head, float lgf2, float lgb2, LAS unsigned char* lds) {
;     ...
;   for (int it = 0; it < 4; ++it) { const int q = tid + it * 512, j = q >> 4, c = q & 15;
;     const u32x4 v = *(const u32x4*)(Kb + (size_t)(row0 + j) * 512 + head * 128 + c * 8);
;     const float zf = __builtin_amdgcn_exp2f(lgf2 * (float)(127 - j)), zb = __builtin_amdgcn_exp2f(lgb2 * (float)j);
;     u32x4 of, ob;
; #pragma unroll
;     for (int i = 0; i < 4; ++i) { const float a = bf_lo(v[i]), b = bf_hi(v[i]); of[i] = cvt_pk_bf16(a * zf, b * zf); ob[i] = cvt_pk_bf16(a * zb, b * zb); }
;     *(LAS u32x4*)(lds + OKF + j * KS + c * 16) = of; *(LAS u32x4*)(lds + OKB + j * KS + c * 16) = ob; }
;   __syncthreads();
;   const int i16 = l & 15, q4 = i16 >> 2, p4 = i16 & 3, G1 = (l >> 4) & 1, h = l >> 5;
;   const unsigned cofs = (unsigned)(16 * G1 + 4 * p4) * 2u;
;   f32x16 af[4], ab[4];
; #pragma unroll
;   for (int i = 0; i < 4; ++i) { af[i] = (f32x16){}; ab[i] = (f32x16){}; }
;   for (int ks = 0; ks < 8; ++ks) {
;     const unsigned r = (unsigned)(16 * ks + 8 * h + q4);
;     const bf16x8 Bv = tr_frag(lds, r * VS + w * 64 + cofs, (r + 4) * VS + w * 64 + cofs);
	v_lshlrev_b32_e32 v18, 16, v0
	v_and_b32_e32 v19, 0xffff0000, v0
	v_pk_mul_f32 v[20:21], v[8:9], v[18:19] op_sel_hi:[0,1]
	v_cvt_pk_bf16_f32 v0, v20, v21
	v_lshlrev_b32_e32 v20, 16, v1
	v_and_b32_e32 v21, 0xffff0000, v1
	v_pk_mul_f32 v[18:19], v[12:13], v[18:19] op_sel_hi:[0,1]
	v_pk_mul_f32 v[22:23], v[8:9], v[20:21] op_sel_hi:[0,1]
	v_pk_mul_f32 v[20:21], v[12:13], v[20:21] op_sel_hi:[0,1]
	v_cvt_pk_bf16_f32 v18, v18, v19
	v_cvt_pk_bf16_f32 v19, v20, v21
	v_lshlrev_b32_e32 v20, 16, v2
	v_and_b32_e32 v21, 0xffff0000, v2
	v_cvt_pk_bf16_f32 v1, v22, v23
	v_pk_mul_f32 v[22:23], v[8:9], v[20:21] op_sel_hi:[0,1]
	v_cvt_pk_bf16_f32 v2, v22, v23
	v_lshlrev_b32_e32 v22, 16, v3
	v_and_b32_e32 v23, 0xffff0000, v3
	v_pk_mul_f32 v[8:9], v[8:9], v[22:23] op_sel_hi:[0,1]
	v_pk_mul_f32 v[20:21], v[12:13], v[20:21] op_sel_hi:[0,1]
	v_cvt_pk_bf16_f32 v3, v8, v9
	v_pk_mul_f32 v[8:9], v[12:13], v[22:23] op_sel_hi:[0,1]
	v_cvt_pk_bf16_f32 v20, v20, v21
	v_cvt_pk_bf16_f32 v21, v8, v9
	v_mul_lo_u32 v8, v47, s13
	v_add_u32_e32 v9, v25, v8
	ds_write_b128 v9, v[0:3]
	v_sub_u32_e32 v0, 0x7f, v29
	v_cvt_f32_i32_e32 v0, v0
	v_cvt_f32_i32_e32 v2, v29
	v_add_u32_e32 v1, v28, v8
	ds_write_b128 v1, v[18:21]
	v_mul_f32_e32 v0, v10, v0
	v_exp_f32_e32 v8, v0
	v_mul_f32_e32 v0, v11, v2
	v_exp_f32_e32 v18, v0
	s_waitcnt vmcnt(1)
	v_mov_b64_e32 v[14:15], v[182:183]
	v_mov_b64_e32 v[16:17], v[184:185]
	v_lshlrev_b32_e32 v2, 16, v14
	v_and_b32_e32 v3, 0xffff0000, v14
	v_pk_mul_f32 v[0:1], v[8:9], v[2:3] op_sel_hi:[0,1]
	v_pk_mul_f32 v[2:3], v[18:19], v[2:3] op_sel_hi:[0,1]
	v_cvt_pk_bf16_f32 v12, v2, v3
	v_lshlrev_b32_e32 v2, 16, v15
	v_and_b32_e32 v3, 0xffff0000, v15
	v_pk_mul_f32 v[14:15], v[8:9], v[2:3] op_sel_hi:[0,1]
	v_cvt_pk_bf16_f32 v0, v0, v1
	v_cvt_pk_bf16_f32 v1, v14, v15
	v_pk_mul_f32 v[2:3], v[18:19], v[2:3] op_sel_hi:[0,1]
	v_lshlrev_b32_e32 v14, 16, v16
	v_and_b32_e32 v15, 0xffff0000, v16
	v_lshlrev_b32_e32 v16, 16, v17
	v_and_b32_e32 v17, 0xffff0000, v17
	v_cvt_pk_bf16_f32 v13, v2, v3
	v_pk_mul_f32 v[2:3], v[8:9], v[14:15] op_sel_hi:[0,1]
	v_pk_mul_f32 v[8:9], v[8:9], v[16:17] op_sel_hi:[0,1]
	v_cvt_pk_bf16_f32 v2, v2, v3
	v_pk_mul_f32 v[14:15], v[18:19], v[14:15] op_sel_hi:[0,1]
	v_cvt_pk_bf16_f32 v3, v8, v9
	v_pk_mul_f32 v[8:9], v[18:19], v[16:17] op_sel_hi:[0,1]
	v_cvt_pk_bf16_f32 v14, v14, v15
	v_cvt_pk_bf16_f32 v15, v8, v9
	v_mul_lo_u32 v8, v29, s13
	v_add_u32_e32 v9, v25, v8
	ds_write_b128 v9, v[0:3]
	v_sub_u32_e32 v0, 0x7f, v24
	v_cvt_f32_i32_e32 v0, v0
	v_cvt_f32_i32_e32 v2, v24
	v_add_u32_e32 v1, v28, v8
	ds_write_b128 v1, v[12:15]
	v_mul_f32_e32 v0, v10, v0
	v_exp_f32_e32 v8, v0
	v_mul_f32_e32 v0, v11, v2
	v_exp_f32_e32 v10, v0
	s_waitcnt vmcnt(0)
	v_mov_b64_e32 v[4:5], v[186:187]
	v_mov_b64_e32 v[6:7], v[188:189]
	v_lshlrev_b32_e32 v2, 16, v4
	v_and_b32_e32 v3, 0xffff0000, v4
	v_pk_mul_f32 v[0:1], v[8:9], v[2:3] op_sel_hi:[0,1]
	v_pk_mul_f32 v[2:3], v[10:11], v[2:3] op_sel_hi:[0,1]
	v_cvt_pk_bf16_f32 v4, v2, v3
	v_lshlrev_b32_e32 v2, 16, v5
	v_and_b32_e32 v3, 0xffff0000, v5
	v_pk_mul_f32 v[12:13], v[8:9], v[2:3] op_sel_hi:[0,1]
	v_cvt_pk_bf16_f32 v0, v0, v1
	v_cvt_pk_bf16_f32 v1, v12, v13
	v_pk_mul_f32 v[2:3], v[10:11], v[2:3] op_sel_hi:[0,1]
	v_lshlrev_b32_e32 v12, 16, v6
	v_and_b32_e32 v13, 0xffff0000, v6
	v_cvt_pk_bf16_f32 v5, v2, v3
	v_pk_mul_f32 v[2:3], v[8:9], v[12:13] op_sel_hi:[0,1]
	v_pk_mul_f32 v[12:13], v[10:11], v[12:13] op_sel_hi:[0,1]
	v_cvt_pk_bf16_f32 v6, v12, v13
	v_lshlrev_b32_e32 v12, 16, v7
	v_and_b32_e32 v13, 0xffff0000, v7
	v_pk_mul_f32 v[8:9], v[8:9], v[12:13] op_sel_hi:[0,1]
	v_cvt_pk_bf16_f32 v2, v2, v3
	v_cvt_pk_bf16_f32 v3, v8, v9
	v_pk_mul_f32 v[8:9], v[10:11], v[12:13] op_sel_hi:[0,1]
	v_cvt_pk_bf16_f32 v7, v8, v9
	v_mul_lo_u32 v8, v24, s13
	v_add_u32_e32 v9, v25, v8
	ds_write_b128 v9, v[0:3]
	v_add_u32_e32 v0, v28, v8
	ds_write_b128 v0, v[4:7]
	v_lshrrev_b32_e32 v0, 2, v152
	v_and_b32_e32 v1, 16, v152
	v_lshlrev_b32_e32 v2, 2, v152
	v_and_or_b32 v1, v2, 12, v1
	v_and_b32_e32 v5, 11, v0
	v_and_b32_e32 v0, 0xffffffc0, v152
	v_lshlrev_b32_e32 v4, 1, v1
	v_add_u32_e32 v6, 0, v0
	v_mul_u32_u24_e32 v0, 0x140, v5
	v_add3_u32 v154, 0, v0, v4
	v_mul_u32_u24_e32 v5, 0x240, v5
	v_add_u32_e32 v12, 0x12000, v154
	v_add3_u32 v132, v6, v4, v5
	v_add_u32_e32 v14, 0x1c000, v154
	v_add_u32_e32 v15, 0x1c500, v154
	s_waitcnt lgkmcnt(0)
	s_barrier
; __device__ __forceinline__ f32x16 mfma32(bf16x8 a, bf16x8 b, f32x16 c) { return __builtin_amdgcn_mfma_f32_32x32x16_bf16(a, b, c, 0, 0, 0); }
; __device__ void ret_state_item(const bf16_t* __restrict__ Kb, const bf16_t* __restrict__ Vb, bf16_t* __restrict__ STf, bf16_t* __restrict__ STb,
;                                int cidx, int head, float lgf2, float lgb2, LAS unsigned char* lds) {
;     ...
;   for (int ks = 0; ks < 8; ++ks) {
;     const unsigned r = (unsigned)(16 * ks + 8 * h + q4);
;     const bf16x8 Bv = tr_frag(lds, r * VS + w * 64 + cofs, (r + 4) * VS + w * 64 + cofs);
; #pragma unroll
;     for (int dt = 0; dt < 4; ++dt) {
;       const bf16x8 Af = tr_frag(lds, OKF + r * KS + dt * 64 + cofs, OKF + (r + 4) * KS + dt * 64 + cofs);
;       const bf16x8 Ab = tr_frag(lds, OKB + r * KS + dt * 64 + cofs, OKB + (r + 4) * KS + dt * 64 + cofs);
;       af[dt] = mfma32(Af, Bv, af[dt]); ab[dt] = mfma32(Ab, Bv, ab[dt]);
;     }
;   }
	v_add_u32_e32 v13, 0x12500, v154
	ds_read_b64_tr_b16 v[0:1], v12
	ds_read_b64_tr_b16 v[2:3], v13
	ds_read_b64_tr_b16 v[4:5], v132
	ds_read_b64_tr_b16 v[6:7], v132 offset:2304
	ds_read_b64_tr_b16 v[8:9], v14
	ds_read_b64_tr_b16 v[10:11], v15
	s_waitcnt lgkmcnt(2)
	v_mfma_f32_32x32x16_bf16 v[112:127], v[0:3], v[4:7], 0
	v_add_u32_e32 v133, 0x13400, v154
	v_add_u32_e32 v135, 0x1d400, v154
	v_add_u32_e32 v155, 0x1d900, v154
	v_add_u32_e32 v134, 0x13900, v154
	v_readlane_b32 s12, v250, 51
	v_readlane_b32 s13, v250, 52
	s_waitcnt lgkmcnt(0)
	v_mfma_f32_32x32x16_bf16 v[96:111], v[8:11], v[4:7], 0
	ds_read_b64_tr_b16 v[0:1], v12 offset:64
	ds_read_b64_tr_b16 v[2:3], v13 offset:64
	ds_read_b64_tr_b16 v[8:9], v14 offset:64
	ds_read_b64_tr_b16 v[10:11], v15 offset:64
	s_waitcnt lgkmcnt(2)
	v_mfma_f32_32x32x16_bf16 v[80:95], v[0:3], v[4:7], 0
	s_waitcnt lgkmcnt(0)
	v_mfma_f32_32x32x16_bf16 v[64:79], v[8:11], v[4:7], 0
	ds_read_b64_tr_b16 v[0:1], v12 offset:128
	ds_read_b64_tr_b16 v[2:3], v13 offset:128
	ds_read_b64_tr_b16 v[8:9], v14 offset:128
	ds_read_b64_tr_b16 v[10:11], v15 offset:128
	s_waitcnt lgkmcnt(2)
	v_mfma_f32_32x32x16_bf16 v[48:63], v[0:3], v[4:7], 0
	s_waitcnt lgkmcnt(0)
	v_mfma_f32_32x32x16_bf16 v[16:31], v[8:11], v[4:7], 0
	ds_read_b64_tr_b16 v[0:1], v12 offset:192
	ds_read_b64_tr_b16 v[2:3], v13 offset:192
	ds_read_b64_tr_b16 v[8:9], v14 offset:192
	ds_read_b64_tr_b16 v[10:11], v15 offset:192
	ds_read_b64_tr_b16 v[128:129], v133
	ds_read_b64_tr_b16 v[130:131], v134
	ds_read_b64_tr_b16 v[156:157], v132 offset:9216
	ds_read_b64_tr_b16 v[158:159], v132 offset:11520
	ds_read_b64_tr_b16 v[174:175], v135
	ds_read_b64_tr_b16 v[176:177], v155
	s_waitcnt lgkmcnt(2)
	v_mfma_f32_32x32x16_bf16 v[112:127], v[128:131], v[156:159], v[112:127]
	s_waitcnt lgkmcnt(0)
	v_mfma_f32_32x32x16_bf16 v[96:111], v[174:177], v[156:159], v[96:111]
	ds_read_b64_tr_b16 v[128:129], v133 offset:64
	ds_read_b64_tr_b16 v[130:131], v134 offset:64
	ds_read_b64_tr_b16 v[174:175], v135 offset:64
	ds_read_b64_tr_b16 v[176:177], v155 offset:64
	s_waitcnt lgkmcnt(2)
	v_mfma_f32_32x32x16_bf16 v[80:95], v[128:131], v[156:159], v[80:95]
	s_waitcnt lgkmcnt(0)
	v_mfma_f32_32x32x16_bf16 v[64:79], v[174:177], v[156:159], v[64:79]
	ds_read_b64_tr_b16 v[128:129], v133 offset:128
	ds_read_b64_tr_b16 v[130:131], v134 offset:128
	ds_read_b64_tr_b16 v[174:175], v135 offset:128
	ds_read_b64_tr_b16 v[176:177], v155 offset:128
	s_waitcnt lgkmcnt(2)
	v_mfma_f32_32x32x16_bf16 v[48:63], v[128:131], v[156:159], v[48:63]
	s_waitcnt lgkmcnt(0)
	v_mfma_f32_32x32x16_bf16 v[16:31], v[174:177], v[156:159], v[16:31]
	ds_read_b64_tr_b16 v[128:129], v133 offset:192
	ds_read_b64_tr_b16 v[130:131], v134 offset:192
	ds_read_b64_tr_b16 v[174:175], v135 offset:192
	ds_read_b64_tr_b16 v[176:177], v155 offset:192
	v_add_u32_e32 v133, 0x14800, v154
	v_add_u32_e32 v135, 0x1e800, v154
	v_add_u32_e32 v155, 0x1ed00, v154
	v_add_u32_e32 v134, 0x14d00, v154
	v_mfma_f32_32x32x16_bf16 v[32:47], v[0:3], v[4:7], 0
	v_mfma_f32_32x32x16_bf16 v[0:15], v[8:11], v[4:7], 0
	s_waitcnt lgkmcnt(2)
	v_mfma_f32_32x32x16_bf16 v[32:47], v[128:131], v[156:159], v[32:47]
	s_waitcnt lgkmcnt(0)
	v_mfma_f32_32x32x16_bf16 v[0:15], v[174:177], v[156:159], v[0:15]
	ds_read_b64_tr_b16 v[128:129], v133
	ds_read_b64_tr_b16 v[130:131], v134
	ds_read_b64_tr_b16 v[156:157], v132 offset:18432
	ds_read_b64_tr_b16 v[158:159], v132 offset:20736
	ds_read_b64_tr_b16 v[174:175], v135
	ds_read_b64_tr_b16 v[176:177], v155
	s_waitcnt lgkmcnt(2)
	v_mfma_f32_32x32x16_bf16 v[112:127], v[128:131], v[156:159], v[112:127]
	s_waitcnt lgkmcnt(0)
	v_mfma_f32_32x32x16_bf16 v[96:111], v[174:177], v[156:159], v[96:111]
	ds_read_b64_tr_b16 v[128:129], v133 offset:64
	ds_read_b64_tr_b16 v[130:131], v134 offset:64
	ds_read_b64_tr_b16 v[174:175], v135 offset:64
	ds_read_b64_tr_b16 v[176:177], v155 offset:64
	s_waitcnt lgkmcnt(2)
	v_mfma_f32_32x32x16_bf16 v[80:95], v[128:131], v[156:159], v[80:95]
	s_waitcnt lgkmcnt(0)
	v_mfma_f32_32x32x16_bf16 v[64:79], v[174:177], v[156:159], v[64:79]
	ds_read_b64_tr_b16 v[128:129], v133 offset:128
	ds_read_b64_tr_b16 v[130:131], v134 offset:128
	ds_read_b64_tr_b16 v[174:175], v135 offset:128
	ds_read_b64_tr_b16 v[176:177], v155 offset:128
	s_waitcnt lgkmcnt(2)
	v_mfma_f32_32x32x16_bf16 v[48:63], v[128:131], v[156:159], v[48:63]
	s_waitcnt lgkmcnt(0)
	v_mfma_f32_32x32x16_bf16 v[16:31], v[174:177], v[156:159], v[16:31]
	ds_read_b64_tr_b16 v[128:129], v133 offset:192
	ds_read_b64_tr_b16 v[130:131], v134 offset:192
	ds_read_b64_tr_b16 v[174:175], v135 offset:192
	ds_read_b64_tr_b16 v[176:177], v155 offset:192
	v_add_u32_e32 v133, 0x15c00, v154
	v_add_u32_e32 v135, 0x1fc00, v154
	v_add_u32_e32 v155, 0x20100, v154
	v_add_u32_e32 v134, 0x16100, v154
	s_waitcnt lgkmcnt(2)
	v_mfma_f32_32x32x16_bf16 v[32:47], v[128:131], v[156:159], v[32:47]
	s_waitcnt lgkmcnt(0)
	v_mfma_f32_32x32x16_bf16 v[0:15], v[174:177], v[156:159], v[0:15]
	ds_read_b64_tr_b16 v[128:129], v133
	ds_read_b64_tr_b16 v[130:131], v134
	ds_read_b64_tr_b16 v[156:157], v132 offset:27648
	ds_read_b64_tr_b16 v[158:159], v132 offset:29952
	ds_read_b64_tr_b16 v[174:175], v135
	ds_read_b64_tr_b16 v[176:177], v155
	s_waitcnt lgkmcnt(2)
	v_mfma_f32_32x32x16_bf16 v[112:127], v[128:131], v[156:159], v[112:127]
	s_waitcnt lgkmcnt(0)
	v_mfma_f32_32x32x16_bf16 v[96:111], v[174:177], v[156:159], v[96:111]
	ds_read_b64_tr_b16 v[128:129], v133 offset:64
	ds_read_b64_tr_b16 v[130:131], v134 offset:64
	ds_read_b64_tr_b16 v[174:175], v135 offset:64
	ds_read_b64_tr_b16 v[176:177], v155 offset:64
	s_waitcnt lgkmcnt(2)
	v_mfma_f32_32x32x16_bf16 v[80:95], v[128:131], v[156:159], v[80:95]
	s_waitcnt lgkmcnt(0)
; __device__ __forceinline__ f32x16 mfma32(bf16x8 a, bf16x8 b, f32x16 c) { return __builtin_amdgcn_mfma_f32_32x32x16_bf16(a, b, c, 0, 0, 0); }
; __device__ void ret_state_item(const bf16_t* __restrict__ Kb, const bf16_t* __restrict__ Vb, bf16_t* __restrict__ STf, bf16_t* __restrict__ STb,
;                                int cidx, int head, float lgf2, float lgb2, LAS unsigned char* lds) {
;     ...
;   for (int ks = 0; ks < 8; ++ks) {
;     const unsigned r = (unsigned)(16 * ks + 8 * h + q4);
;     const bf16x8 Bv = tr_frag(lds, r * VS + w * 64 + cofs, (r + 4) * VS + w * 64 + cofs);
; #pragma unroll
;     for (int dt = 0; dt < 4; ++dt) {
;       const bf16x8 Af = tr_frag(lds, OKF + r * KS + dt * 64 + cofs, OKF + (r + 4) * KS + dt * 64 + cofs);
;       const bf16x8 Ab = tr_frag(lds, OKB + r * KS + dt * 64 + cofs, OKB + (r + 4) * KS + dt * 64 + cofs);
;       af[dt] = mfma32(Af, Bv, af[dt]); ab[dt] = mfma32(Ab, Bv, ab[dt]);
;     }
;   }
	v_mfma_f32_32x32x16_bf16 v[64:79], v[174:177], v[156:159], v[64:79]
	ds_read_b64_tr_b16 v[128:129], v133 offset:128
	ds_read_b64_tr_b16 v[130:131], v134 offset:128
	ds_read_b64_tr_b16 v[174:175], v135 offset:128
	ds_read_b64_tr_b16 v[176:177], v155 offset:128
	s_waitcnt lgkmcnt(2)
	v_mfma_f32_32x32x16_bf16 v[48:63], v[128:131], v[156:159], v[48:63]
	s_waitcnt lgkmcnt(0)
	v_mfma_f32_32x32x16_bf16 v[16:31], v[174:177], v[156:159], v[16:31]
	ds_read_b64_tr_b16 v[128:129], v133 offset:192
	ds_read_b64_tr_b16 v[130:131], v134 offset:192
	ds_read_b64_tr_b16 v[174:175], v135 offset:192
	ds_read_b64_tr_b16 v[176:177], v155 offset:192
	v_add_u32_e32 v133, 0x17000, v154
	v_add_u32_e32 v135, 0x21000, v154
	v_add_u32_e32 v155, 0x21500, v154
	v_add_u32_e32 v134, 0x17500, v154
	s_waitcnt lgkmcnt(2)
	v_mfma_f32_32x32x16_bf16 v[32:47], v[128:131], v[156:159], v[32:47]
	s_waitcnt lgkmcnt(0)
	v_mfma_f32_32x32x16_bf16 v[0:15], v[174:177], v[156:159], v[0:15]
	ds_read_b64_tr_b16 v[128:129], v133
	ds_read_b64_tr_b16 v[130:131], v134
	ds_read_b64_tr_b16 v[156:157], v132 offset:36864
	ds_read_b64_tr_b16 v[158:159], v132 offset:39168
	ds_read_b64_tr_b16 v[174:175], v135
	ds_read_b64_tr_b16 v[176:177], v155
	s_waitcnt lgkmcnt(2)
	v_mfma_f32_32x32x16_bf16 v[112:127], v[128:131], v[156:159], v[112:127]
	s_waitcnt lgkmcnt(0)
	v_mfma_f32_32x32x16_bf16 v[96:111], v[174:177], v[156:159], v[96:111]
	ds_read_b64_tr_b16 v[128:129], v133 offset:64
	ds_read_b64_tr_b16 v[130:131], v134 offset:64
	ds_read_b64_tr_b16 v[174:175], v135 offset:64
	ds_read_b64_tr_b16 v[176:177], v155 offset:64
	s_waitcnt lgkmcnt(2)
	v_mfma_f32_32x32x16_bf16 v[80:95], v[128:131], v[156:159], v[80:95]
	s_waitcnt lgkmcnt(0)
	v_mfma_f32_32x32x16_bf16 v[64:79], v[174:177], v[156:159], v[64:79]
	ds_read_b64_tr_b16 v[128:129], v133 offset:128
	ds_read_b64_tr_b16 v[130:131], v134 offset:128
	ds_read_b64_tr_b16 v[174:175], v135 offset:128
	ds_read_b64_tr_b16 v[176:177], v155 offset:128
	s_waitcnt lgkmcnt(2)
	v_mfma_f32_32x32x16_bf16 v[48:63], v[128:131], v[156:159], v[48:63]
	s_waitcnt lgkmcnt(0)
	v_mfma_f32_32x32x16_bf16 v[16:31], v[174:177], v[156:159], v[16:31]
	ds_read_b64_tr_b16 v[128:129], v133 offset:192
	ds_read_b64_tr_b16 v[130:131], v134 offset:192
	ds_read_b64_tr_b16 v[174:175], v135 offset:192
	ds_read_b64_tr_b16 v[176:177], v155 offset:192
	v_add_u32_e32 v133, 0x18400, v154
	v_add_u32_e32 v135, 0x22400, v154
	v_add_u32_e32 v155, 0x22900, v154
	v_add_u32_e32 v134, 0x18900, v154
	s_waitcnt lgkmcnt(2)
	v_mfma_f32_32x32x16_bf16 v[32:47], v[128:131], v[156:159], v[32:47]
	s_waitcnt lgkmcnt(0)
	v_mfma_f32_32x32x16_bf16 v[0:15], v[174:177], v[156:159], v[0:15]
	ds_read_b64_tr_b16 v[128:129], v133
	ds_read_b64_tr_b16 v[130:131], v134
	ds_read_b64_tr_b16 v[156:157], v132 offset:46080
	ds_read_b64_tr_b16 v[158:159], v132 offset:48384
	ds_read_b64_tr_b16 v[174:175], v135
	ds_read_b64_tr_b16 v[176:177], v155
	s_waitcnt lgkmcnt(2)
	v_mfma_f32_32x32x16_bf16 v[112:127], v[128:131], v[156:159], v[112:127]
	s_waitcnt lgkmcnt(0)
	v_mfma_f32_32x32x16_bf16 v[96:111], v[174:177], v[156:159], v[96:111]
	ds_read_b64_tr_b16 v[128:129], v133 offset:64
	ds_read_b64_tr_b16 v[130:131], v134 offset:64
	ds_read_b64_tr_b16 v[174:175], v135 offset:64
	ds_read_b64_tr_b16 v[176:177], v155 offset:64
	s_waitcnt lgkmcnt(2)
	v_mfma_f32_32x32x16_bf16 v[80:95], v[128:131], v[156:159], v[80:95]
	s_waitcnt lgkmcnt(0)
	v_mfma_f32_32x32x16_bf16 v[64:79], v[174:177], v[156:159], v[64:79]
	ds_read_b64_tr_b16 v[128:129], v133 offset:128
	ds_read_b64_tr_b16 v[130:131], v134 offset:128
	ds_read_b64_tr_b16 v[174:175], v135 offset:128
	ds_read_b64_tr_b16 v[176:177], v155 offset:128
	s_waitcnt lgkmcnt(2)
	v_mfma_f32_32x32x16_bf16 v[48:63], v[128:131], v[156:159], v[48:63]
	s_waitcnt lgkmcnt(0)
	v_mfma_f32_32x32x16_bf16 v[16:31], v[174:177], v[156:159], v[16:31]
	ds_read_b64_tr_b16 v[128:129], v133 offset:192
	ds_read_b64_tr_b16 v[130:131], v134 offset:192
	ds_read_b64_tr_b16 v[174:175], v135 offset:192
	ds_read_b64_tr_b16 v[176:177], v155 offset:192
	v_add_u32_e32 v133, 0x19800, v154
	v_add_u32_e32 v135, 0x23800, v154
	v_add_u32_e32 v155, 0x23d00, v154
	v_add_u32_e32 v134, 0x19d00, v154
	s_waitcnt lgkmcnt(2)
	v_mfma_f32_32x32x16_bf16 v[32:47], v[128:131], v[156:159], v[32:47]
	s_waitcnt lgkmcnt(0)
	v_mfma_f32_32x32x16_bf16 v[0:15], v[174:177], v[156:159], v[0:15]
	ds_read_b64_tr_b16 v[128:129], v133
	ds_read_b64_tr_b16 v[130:131], v134
	ds_read_b64_tr_b16 v[174:175], v132 offset:55296
	ds_read_b64_tr_b16 v[176:177], v132 offset:57600
	ds_read_b64_tr_b16 v[156:157], v135
	ds_read_b64_tr_b16 v[158:159], v155
	s_waitcnt lgkmcnt(2)
	v_mfma_f32_32x32x16_bf16 v[112:127], v[128:131], v[174:177], v[112:127]
	s_waitcnt lgkmcnt(0)
	v_mfma_f32_32x32x16_bf16 v[96:111], v[156:159], v[174:177], v[96:111]
	ds_read_b64_tr_b16 v[128:129], v133 offset:64
	ds_read_b64_tr_b16 v[130:131], v134 offset:64
	ds_read_b64_tr_b16 v[156:157], v135 offset:64
	ds_read_b64_tr_b16 v[158:159], v155 offset:64
	s_waitcnt lgkmcnt(2)
	v_mfma_f32_32x32x16_bf16 v[80:95], v[128:131], v[174:177], v[80:95]
	s_waitcnt lgkmcnt(0)
	v_mfma_f32_32x32x16_bf16 v[64:79], v[156:159], v[174:177], v[64:79]
	ds_read_b64_tr_b16 v[128:129], v133 offset:128
	ds_read_b64_tr_b16 v[130:131], v134 offset:128
	ds_read_b64_tr_b16 v[156:157], v135 offset:128
	ds_read_b64_tr_b16 v[158:159], v155 offset:128
	s_waitcnt lgkmcnt(2)
	v_mfma_f32_32x32x16_bf16 v[48:63], v[128:131], v[174:177], v[48:63]
	ds_read_b64_tr_b16 v[128:129], v133 offset:192
	ds_read_b64_tr_b16 v[130:131], v134 offset:192
	ds_read_b64_tr_b16 v[178:179], v135 offset:192
	ds_read_b64_tr_b16 v[180:181], v155 offset:192
	v_add_u32_e32 v134, 0x900, v132
	v_add_u32_e32 v155, 0x1b100, v154
	s_waitcnt lgkmcnt(4)
; __device__ __forceinline__ u32x2 pack4(float a, float b, float c, float d) { u32x2 o; o[0] = cvt_pk_bf16(a, b); o[1] = cvt_pk_bf16(c, d); return o; }
; __device__ __forceinline__ f32x16 mfma32(bf16x8 a, bf16x8 b, f32x16 c) { return __builtin_amdgcn_mfma_f32_32x32x16_bf16(a, b, c, 0, 0, 0); }
; __device__ __forceinline__ void store_tile16(bf16_t* p, const f32x16& a, float sc, int h) {
; #pragma unroll
;   for (int gp = 0; gp < 2; ++gp) {
;     u32x2 A = pack4(a[8 * gp] * sc, a[8 * gp + 1] * sc, a[8 * gp + 2] * sc, a[8 * gp + 3] * sc), B = pack4(a[8 * gp + 4] * sc, a[8 * gp + 5] * sc, a[8 * gp + 6] * sc, a[8 * gp + 7] * sc);
;     const auto r0 = __builtin_amdgcn_permlane32_swap(A[0], B[0], false, false), r1 = __builtin_amdgcn_permlane32_swap(A[1], B[1], false, false);
;     u32x4 o = {r0[0], r1[0], r0[1], r1[1]};
;     *(u32x4*)(p + 16 * gp + 8 * h) = o;
; __device__ void ret_state_item(const bf16_t* __restrict__ Kb, const bf16_t* __restrict__ Vb, bf16_t* __restrict__ STf, bf16_t* __restrict__ STb,
;                                int cidx, int head, float lgf2, float lgb2, LAS unsigned char* lds) {
;     ...
;   for (int ks = 0; ks < 8; ++ks) {
;     const unsigned r = (unsigned)(16 * ks + 8 * h + q4);
;     const bf16x8 Bv = tr_frag(lds, r * VS + w * 64 + cofs, (r + 4) * VS + w * 64 + cofs);
; #pragma unroll
;     for (int dt = 0; dt < 4; ++dt) {
;       const bf16x8 Af = tr_frag(lds, OKF + r * KS + dt * 64 + cofs, OKF + (r + 4) * KS + dt * 64 + cofs);
;       const bf16x8 Ab = tr_frag(lds, OKB + r * KS + dt * 64 + cofs, OKB + (r + 4) * KS + dt * 64 + cofs);
;       af[dt] = mfma32(Af, Bv, af[dt]); ab[dt] = mfma32(Ab, Bv, ab[dt]);
;     }
;   }
;   const size_t ob = ((size_t)(cidx * 4 + head) * 256 + w * 32 + (l & 31)) * 128;
; #pragma unroll
;   for (int dt = 0; dt < 4; ++dt) { store_tile16(STf + ob + dt * 32, af[dt], 1.f, h); store_tile16(STb + ob + dt * 32, ab[dt], 1.f, h); }
	v_mfma_f32_32x32x16_bf16 v[16:31], v[156:159], v[174:177], v[16:31]
	v_add_u32_e32 v156, 0x1ac00, v154
	v_add_u32_e32 v157, 0x24c00, v154
	v_add_u32_e32 v158, 0x25100, v154
	s_waitcnt lgkmcnt(2)
	v_mfma_f32_32x32x16_bf16 v[32:47], v[128:131], v[174:177], v[32:47]
	ds_read_b64_tr_b16 v[128:129], v156
	ds_read_b64_tr_b16 v[130:131], v155
	ds_read_b64_tr_b16 v[132:133], v132 offset:64512
	ds_read_b64_tr_b16 v[134:135], v134 offset:64512
	s_waitcnt lgkmcnt(4)
	v_mfma_f32_32x32x16_bf16 v[0:15], v[178:181], v[174:177], v[0:15]
	ds_read_b64_tr_b16 v[174:175], v157
	ds_read_b64_tr_b16 v[176:177], v158
	s_waitcnt lgkmcnt(2)
	v_mfma_f32_32x32x16_bf16 v[112:127], v[128:131], v[132:135], v[112:127]
	s_waitcnt lgkmcnt(0)
	v_mfma_f32_32x32x16_bf16 v[96:111], v[174:177], v[132:135], v[96:111]
	ds_read_b64_tr_b16 v[128:129], v156 offset:64
	ds_read_b64_tr_b16 v[130:131], v155 offset:64
	ds_read_b64_tr_b16 v[174:175], v157 offset:64
	ds_read_b64_tr_b16 v[176:177], v158 offset:64
	s_nop 5
	v_cvt_pk_bf16_f32 v112, v112, v113
	v_cvt_pk_bf16_f32 v113, v114, v115
	v_cvt_pk_bf16_f32 v114, v116, v117
	v_cvt_pk_bf16_f32 v115, v118, v119
	s_nop 0
	v_permlane32_swap_b32_e32 v112, v114
	s_waitcnt lgkmcnt(2)
	v_mfma_f32_32x32x16_bf16 v[80:95], v[128:131], v[132:135], v[80:95]
	v_cvt_pk_bf16_f32 v96, v96, v97
	v_cvt_pk_bf16_f32 v97, v98, v99
	v_cvt_pk_bf16_f32 v98, v100, v101
	v_cvt_pk_bf16_f32 v99, v102, v103
	v_permlane32_swap_b32_e32 v113, v115
	v_permlane32_swap_b32_e32 v96, v98
	s_waitcnt lgkmcnt(0)
	v_mfma_f32_32x32x16_bf16 v[64:79], v[174:177], v[132:135], v[64:79]
	ds_read_b64_tr_b16 v[128:129], v156 offset:128
	ds_read_b64_tr_b16 v[130:131], v155 offset:128
	ds_read_b64_tr_b16 v[174:175], v157 offset:128
	ds_read_b64_tr_b16 v[176:177], v158 offset:128
	v_cvt_pk_bf16_f32 v80, v80, v81
	v_cvt_pk_bf16_f32 v81, v82, v83
	v_cvt_pk_bf16_f32 v82, v84, v85
	v_cvt_pk_bf16_f32 v83, v86, v87
	v_permlane32_swap_b32_e32 v97, v99
	s_waitcnt lgkmcnt(2)
	v_mfma_f32_32x32x16_bf16 v[48:63], v[128:131], v[132:135], v[48:63]
	ds_read_b64_tr_b16 v[128:129], v156 offset:192
	ds_read_b64_tr_b16 v[130:131], v155 offset:192
	ds_read_b64_tr_b16 v[154:155], v157 offset:192
	ds_read_b64_tr_b16 v[156:157], v158 offset:192
	v_cvt_pk_bf16_f32 v64, v64, v65
	v_cvt_pk_bf16_f32 v65, v66, v67
	v_cvt_pk_bf16_f32 v66, v68, v69
	v_cvt_pk_bf16_f32 v67, v70, v71
	v_permlane32_swap_b32_e32 v80, v82
	s_waitcnt lgkmcnt(4)
	v_mfma_f32_32x32x16_bf16 v[16:31], v[174:177], v[132:135], v[16:31]
	s_nop 0
	v_cvt_pk_bf16_f32 v48, v48, v49
	v_cvt_pk_bf16_f32 v49, v50, v51
	v_cvt_pk_bf16_f32 v50, v52, v53
	v_cvt_pk_bf16_f32 v51, v54, v55
	v_permlane32_swap_b32_e32 v81, v83
	v_permlane32_swap_b32_e32 v64, v66
	s_waitcnt lgkmcnt(2)
	v_mfma_f32_32x32x16_bf16 v[32:47], v[128:131], v[132:135], v[32:47]
	v_ashrrev_i32_e32 v128, 1, v152
	v_and_b32_e32 v128, 0xffffffe0, v128
	v_ashrrev_i32_e32 v129, 31, v128
	v_or_b32_e32 v128, v128, v153
	v_lshl_add_u64 v[128:129], s[22:23], 0, v[128:129]
	v_lshlrev_b64 v[128:129], 8, v[128:129]
	v_lshl_add_u64 v[130:131], s[12:13], 0, v[128:129]
	s_waitcnt lgkmcnt(0)
	v_mfma_f32_32x32x16_bf16 v[0:15], v[154:157], v[132:135], v[0:15]
	v_readlane_b32 s12, v250, 53
	v_lshrrev_b32_e32 v132, 1, v152
	v_readlane_b32 s13, v250, 54
	v_and_b32_e32 v160, 16, v132
	v_cvt_pk_bf16_f32 v16, v16, v17
	v_lshl_add_u64 v[128:129], s[12:13], 0, v[128:129]
	v_cvt_pk_bf16_f32 v17, v18, v19
	v_cvt_pk_bf16_f32 v18, v20, v21
	v_cvt_pk_bf16_f32 v19, v22, v23
	v_lshl_add_u64 v[128:129], v[128:129], 0, v[160:161]
	v_permlane32_swap_b32_e32 v16, v18
	v_permlane32_swap_b32_e32 v17, v19
	s_barrier
; __device__ __forceinline__ u32x2 pack4(float a, float b, float c, float d) { u32x2 o; o[0] = cvt_pk_bf16(a, b); o[1] = cvt_pk_bf16(c, d); return o; }
; __device__ __forceinline__ void store_tile16(bf16_t* p, const f32x16& a, float sc, int h) {
; #pragma unroll
;   for (int gp = 0; gp < 2; ++gp) {
;     u32x2 A = pack4(a[8 * gp] * sc, a[8 * gp + 1] * sc, a[8 * gp + 2] * sc, a[8 * gp + 3] * sc), B = pack4(a[8 * gp + 4] * sc, a[8 * gp + 5] * sc, a[8 * gp + 6] * sc, a[8 * gp + 7] * sc);
;     const auto r0 = __builtin_amdgcn_permlane32_swap(A[0], B[0], false, false), r1 = __builtin_amdgcn_permlane32_swap(A[1], B[1], false, false);
;     u32x4 o = {r0[0], r1[0], r0[1], r1[1]};
;     *(u32x4*)(p + 16 * gp + 8 * h) = o;
; __device__ void ret_state_item(const bf16_t* __restrict__ Kb, const bf16_t* __restrict__ Vb, bf16_t* __restrict__ STf, bf16_t* __restrict__ STb,
;                                int cidx, int head, float lgf2, float lgb2, LAS unsigned char* lds) {
;     ...
;   const size_t ob = ((size_t)(cidx * 4 + head) * 256 + w * 32 + (l & 31)) * 128;
; #pragma unroll
;   for (int dt = 0; dt < 4; ++dt) { store_tile16(STf + ob + dt * 32, af[dt], 1.f, h); store_tile16(STb + ob + dt * 32, ab[dt], 1.f, h); }
;   __syncthreads();
	v_lshrrev_b32_e32 v176, 6, v152
	v_mul_u32_u24_e32 v176, 0x4400, v176
	v_mul_u32_u24_e32 v178, 0x110, v153
	v_add3_u32 v178, v176, v178, v160
	v_and_b32_e32 v179, 63, v152
	v_lshrrev_b32_e32 v188, 4, v179
	v_and_b32_e32 v189, 15, v179
	v_mul_u32_u24_e32 v188, 0x110, v188
	v_lshl_add_u32 v188, v189, 4, v188
	v_add_u32_e32 v190, v176, v188
	v_add_u32_e32 v191, 0x2200, v190
	v_mov_b32_e32 v176, v178
	v_add_u32_e32 v177, 0x2200, v176
	ds_write_b128 v177, v[16:19] offset:128
	v_readlane_b32 s12, v255, 34
	v_cvt_pk_bf16_f32 v0, v0, v1
	v_cvt_pk_bf16_f32 v16, v24, v25
	v_cvt_pk_bf16_f32 v17, v26, v27
	v_cvt_pk_bf16_f32 v18, v28, v29
	v_cvt_pk_bf16_f32 v19, v30, v31
	s_nop 0
	v_permlane32_swap_b32_e32 v16, v18
	v_permlane32_swap_b32_e32 v17, v19
	ds_write_b128 v177, v[16:19] offset:160
	v_cvt_pk_bf16_f32 v1, v2, v3
	v_cvt_pk_bf16_f32 v2, v4, v5
	v_cvt_pk_bf16_f32 v16, v32, v33
	v_cvt_pk_bf16_f32 v17, v34, v35
	v_cvt_pk_bf16_f32 v18, v36, v37
	v_cvt_pk_bf16_f32 v19, v38, v39
	v_cvt_pk_bf16_f32 v3, v6, v7
	s_add_i32 s6, s6, s12
	v_readlane_b32 s12, v255, 40
	v_lshl_add_u64 v[130:131], v[130:131], 0, v[160:161]
	v_permlane32_swap_b32_e32 v65, v67
	v_permlane32_swap_b32_e32 v48, v50
	v_permlane32_swap_b32_e32 v49, v51
	v_permlane32_swap_b32_e32 v16, v18
	v_permlane32_swap_b32_e32 v17, v19
	v_permlane32_swap_b32_e32 v0, v2
	v_permlane32_swap_b32_e32 v1, v3
	v_readlane_b32 s13, v255, 41
	s_add_u32 s22, s22, s12
	ds_write_b128 v176, v[112:115]
	ds_write_b128 v177, v[96:99]
	ds_write_b128 v176, v[80:83] offset:64
	v_cvt_pk_bf16_f32 v112, v120, v121
	v_cvt_pk_bf16_f32 v113, v122, v123
	v_cvt_pk_bf16_f32 v114, v124, v125
	v_cvt_pk_bf16_f32 v115, v126, v127
	v_cvt_pk_bf16_f32 v96, v104, v105
	v_cvt_pk_bf16_f32 v97, v106, v107
	v_cvt_pk_bf16_f32 v98, v108, v109
	v_cvt_pk_bf16_f32 v99, v110, v111
	v_cvt_pk_bf16_f32 v80, v88, v89
	v_cvt_pk_bf16_f32 v81, v90, v91
	v_cvt_pk_bf16_f32 v82, v92, v93
	v_cvt_pk_bf16_f32 v83, v94, v95
	ds_write_b128 v177, v[64:67] offset:64
	ds_write_b128 v176, v[48:51] offset:128
	ds_write_b128 v176, v[16:19] offset:192
	v_cvt_pk_bf16_f32 v64, v72, v73
	v_cvt_pk_bf16_f32 v65, v74, v75
	v_cvt_pk_bf16_f32 v66, v76, v77
	v_cvt_pk_bf16_f32 v67, v78, v79
	v_cvt_pk_bf16_f32 v48, v56, v57
	v_cvt_pk_bf16_f32 v49, v58, v59
	v_cvt_pk_bf16_f32 v50, v60, v61
	v_cvt_pk_bf16_f32 v51, v62, v63
	v_cvt_pk_bf16_f32 v16, v40, v41
	v_cvt_pk_bf16_f32 v17, v42, v43
	v_cvt_pk_bf16_f32 v18, v44, v45
	v_cvt_pk_bf16_f32 v19, v46, v47
	ds_write_b128 v177, v[0:3] offset:192
	s_addc_u32 s23, s23, s13
	v_permlane32_swap_b32_e32 v112, v114
	v_cvt_pk_bf16_f32 v0, v8, v9
	v_cvt_pk_bf16_f32 v1, v10, v11
	v_cvt_pk_bf16_f32 v2, v12, v13
	v_cvt_pk_bf16_f32 v3, v14, v15
	v_permlane32_swap_b32_e32 v113, v115
	v_permlane32_swap_b32_e32 v96, v98
	v_permlane32_swap_b32_e32 v97, v99
	v_permlane32_swap_b32_e32 v80, v82
	v_permlane32_swap_b32_e32 v81, v83
	v_permlane32_swap_b32_e32 v64, v66
	v_permlane32_swap_b32_e32 v65, v67
	v_permlane32_swap_b32_e32 v48, v50
	v_permlane32_swap_b32_e32 v49, v51
	v_permlane32_swap_b32_e32 v16, v18
	v_permlane32_swap_b32_e32 v17, v19
	v_permlane32_swap_b32_e32 v0, v2
	v_permlane32_swap_b32_e32 v1, v3
	s_cmpk_gt_i32 s7, 0x3ff
	ds_write_b128 v176, v[112:115] offset:32
	ds_write_b128 v177, v[96:99] offset:32
	ds_write_b128 v176, v[80:83] offset:96
	ds_write_b128 v177, v[64:67] offset:96
	ds_write_b128 v176, v[48:51] offset:160
	ds_write_b128 v176, v[16:19] offset:224
	ds_write_b128 v177, v[0:3] offset:224
	s_waitcnt lgkmcnt(0)
	v_lshlrev_b32_e32 v188, 4, v179
	v_lshlrev_b32_e32 v189, 8, v153
	v_sub_u32_e32 v188, v188, v189
	v_sub_u32_e32 v188, v188, v160
	v_ashrrev_i32_e32 v189, 31, v188
	v_lshl_add_u64 v[180:181], v[130:131], 0, v[188:189]
	v_lshl_add_u64 v[184:185], v[128:129], 0, v[188:189]
	s_mov_b32 s72, 0x1000
	s_mov_b32 s73, 0
	v_lshl_add_u64 v[182:183], v[180:181], 0, s[72:73]
	v_lshl_add_u64 v[186:187], v[184:185], 0, s[72:73]
	ds_read_b128 v[0:3], v190
	ds_read_b128 v[4:7], v190 offset:1088
	ds_read_b128 v[8:11], v190 offset:2176
	ds_read_b128 v[12:15], v190 offset:3264
	ds_read_b128 v[16:19], v190 offset:4352
	ds_read_b128 v[20:23], v190 offset:5440
	ds_read_b128 v[24:27], v190 offset:6528
	ds_read_b128 v[28:31], v190 offset:7616
	ds_read_b128 v[32:35], v191
	ds_read_b128 v[36:39], v191 offset:1088
	ds_read_b128 v[40:43], v191 offset:2176
	ds_read_b128 v[44:47], v191 offset:3264
	ds_read_b128 v[48:51], v191 offset:4352
	ds_read_b128 v[52:55], v191 offset:5440
	ds_read_b128 v[56:59], v191 offset:6528
	ds_read_b128 v[60:63], v191 offset:7616
	s_waitcnt lgkmcnt(15)
	global_store_dwordx4 v[180:181], v[0:3], off
	s_waitcnt lgkmcnt(14)
	global_store_dwordx4 v[180:181], v[4:7], off offset:1024
	s_waitcnt lgkmcnt(13)
	global_store_dwordx4 v[180:181], v[8:11], off offset:2048
	s_waitcnt lgkmcnt(12)
	global_store_dwordx4 v[180:181], v[12:15], off offset:3072
	s_waitcnt lgkmcnt(11)
	global_store_dwordx4 v[182:183], v[16:19], off
	s_waitcnt lgkmcnt(10)
	global_store_dwordx4 v[182:183], v[20:23], off offset:1024
	s_waitcnt lgkmcnt(9)
	global_store_dwordx4 v[182:183], v[24:27], off offset:2048
	s_waitcnt lgkmcnt(8)
	global_store_dwordx4 v[182:183], v[28:31], off offset:3072
	s_waitcnt lgkmcnt(7)
	global_store_dwordx4 v[184:185], v[32:35], off
	s_waitcnt lgkmcnt(6)
	global_store_dwordx4 v[184:185], v[36:39], off offset:1024
	s_waitcnt lgkmcnt(5)
	global_store_dwordx4 v[184:185], v[40:43], off offset:2048
	s_waitcnt lgkmcnt(4)
	global_store_dwordx4 v[184:185], v[44:47], off offset:3072
	s_waitcnt lgkmcnt(3)
	global_store_dwordx4 v[186:187], v[48:51], off
	s_waitcnt lgkmcnt(2)
	global_store_dwordx4 v[186:187], v[52:55], off offset:1024
	s_waitcnt lgkmcnt(1)
	global_store_dwordx4 v[186:187], v[56:59], off offset:2048
	s_waitcnt lgkmcnt(0)
	global_store_dwordx4 v[186:187], v[60:63], off offset:3072
	s_barrier
	s_cbranch_scc1 .LBB0_429
